# MLA loop: wave priority 2 from the tile barrier until the first PV group, 0 afterwards
# speedup vs baseline: 1.1318x; 1.0158x over previous
.Lmla_x_cont0:
	v_exp_f32_e32 v116, v116
	v_exp_f32_e32 v117, v117
	v_exp_f32_e32 v118, v118
	v_exp_f32_e32 v119, v119
	v_exp_f32_e32 v132, v132
	v_exp_f32_e32 v133, v133
	v_exp_f32_e32 v134, v134
	v_exp_f32_e32 v135, v135
	s_waitcnt lgkmcnt(8)
	v_exp_f32_e32 v120, v120
	v_mfma_f32_16x16x32_bf16 v[176:179], v[4:7], v[8:11], v[108:111]
	v_exp_f32_e32 v121, v121
	v_mfma_f32_16x16x32_bf16 v[192:195], v[4:7], v[40:43], v[112:115]
	v_exp_f32_e32 v122, v122
	v_mfma_f32_16x16x32_bf16 v[176:179], v[12:15], v[32:35], v[176:179]
	v_exp_f32_e32 v123, v123
	v_mfma_f32_16x16x32_bf16 v[192:195], v[12:15], v[44:47], v[192:195]
	v_exp_f32_e32 v136, v136
	v_mfma_f32_16x16x32_bf16 v[176:179], v[20:23], v[36:39], v[176:179]
	v_exp_f32_e32 v137, v137
	v_mfma_f32_16x16x32_bf16 v[192:195], v[20:23], v[16:19], v[192:195]
	v_exp_f32_e32 v138, v138
	v_exp_f32_e32 v139, v139
	ds_read_b128 v[4:7], v175 offset:21504
	ds_read_b128 v[12:15], v175 offset:25600
	ds_read_b128 v[20:23], v175 offset:29696
	v_cvt_pk_bf16_f32 v116, v116, v117
	v_cvt_pk_bf16_f32 v117, v118, v119
	v_cvt_pk_bf16_f32 v118, v120, v121
	v_cvt_pk_bf16_f32 v119, v122, v123
	v_cvt_pk_bf16_f32 v132, v132, v133
	v_cvt_pk_bf16_f32 v133, v134, v135
	v_cvt_pk_bf16_f32 v134, v136, v137
	v_cvt_pk_bf16_f32 v135, v138, v139
	s_waitcnt lgkmcnt(0)
	v_exp_f32_e32 v124, v124
	v_mfma_f32_16x16x32_bf16 v[180:183], v[4:7], v[8:11], v[108:111]
	v_exp_f32_e32 v125, v125
	v_mfma_f32_16x16x32_bf16 v[196:199], v[4:7], v[40:43], v[112:115]
	v_exp_f32_e32 v126, v126
	v_mfma_f32_16x16x32_bf16 v[180:183], v[12:15], v[32:35], v[180:183]
	v_exp_f32_e32 v127, v127
	v_mfma_f32_16x16x32_bf16 v[196:199], v[12:15], v[44:47], v[196:199]
	v_exp_f32_e32 v140, v140
	v_mfma_f32_16x16x32_bf16 v[180:183], v[20:23], v[36:39], v[180:183]
	v_exp_f32_e32 v141, v141
	v_mfma_f32_16x16x32_bf16 v[196:199], v[20:23], v[16:19], v[196:199]
	v_exp_f32_e32 v142, v142
	v_exp_f32_e32 v143, v143
	ds_read_b128 v[4:7], v175 offset:22528
	ds_read_b128 v[12:15], v175 offset:26624
	ds_read_b128 v[20:23], v175 offset:30720
	ds_read_b64_tr_b16 v[208:209], v167 offset:16384
	ds_read_b64_tr_b16 v[210:211], v167 offset:18432
	ds_read_b64_tr_b16 v[240:241], v171 offset:16384
	ds_read_b64_tr_b16 v[242:243], v171 offset:18432
	ds_read_b64_tr_b16 v[252:253], v172 offset:16384
	ds_read_b64_tr_b16 v[254:255], v172 offset:18432
	s_setprio 0
	v_mfma_f32_16x16x32_bf16 v[104:107], v[248:251], v[116:119], v[104:107]
	v_exp_f32_e32 v128, v128
	v_mfma_f32_16x16x32_bf16 v[88:91], v[248:251], v[132:135], v[88:91]
	v_exp_f32_e32 v129, v129
	v_mfma_f32_16x16x32_bf16 v[100:103], v[24:27], v[116:119], v[100:103]
	v_exp_f32_e32 v130, v130
	v_mfma_f32_16x16x32_bf16 v[80:83], v[24:27], v[132:135], v[80:83]
	v_exp_f32_e32 v131, v131
	v_mfma_f32_16x16x32_bf16 v[96:99], v[28:31], v[116:119], v[96:99]
	v_exp_f32_e32 v144, v144
	v_mfma_f32_16x16x32_bf16 v[76:79], v[28:31], v[132:135], v[76:79]
	v_exp_f32_e32 v145, v145
	s_waitcnt lgkmcnt(6)
	v_mfma_f32_16x16x32_bf16 v[184:187], v[4:7], v[8:11], v[108:111]
	v_exp_f32_e32 v146, v146
	v_exp_f32_e32 v147, v147
	v_mfma_f32_16x16x32_bf16 v[200:203], v[4:7], v[40:43], v[112:115]
	s_nop 0
	v_cvt_pk_bf16_f32 v124, v124, v125
	v_mfma_f32_16x16x32_bf16 v[184:187], v[12:15], v[32:35], v[184:187]
	v_cvt_pk_bf16_f32 v125, v126, v127
	v_cvt_pk_bf16_f32 v126, v128, v129
	v_mfma_f32_16x16x32_bf16 v[200:203], v[12:15], v[44:47], v[200:203]
	v_cvt_pk_bf16_f32 v127, v130, v131
	v_cvt_pk_bf16_f32 v140, v140, v141
	v_mfma_f32_16x16x32_bf16 v[184:187], v[20:23], v[36:39], v[184:187]
	v_cvt_pk_bf16_f32 v141, v142, v143
	v_cvt_pk_bf16_f32 v142, v144, v145
	v_mfma_f32_16x16x32_bf16 v[200:203], v[20:23], v[16:19], v[200:203]
	v_cvt_pk_bf16_f32 v143, v146, v147
	ds_read_b128 v[4:7], v175 offset:23552
	ds_read_b128 v[12:15], v175 offset:27648
	ds_read_b128 v[20:23], v175 offset:31744
	ds_read_b64_tr_b16 v[24:25], v173 offset:16384
	ds_read_b64_tr_b16 v[26:27], v173 offset:18432
	v_mfma_f32_16x16x32_bf16 v[92:95], v[148:151], v[116:119], v[92:95]
	v_mfma_f32_16x16x32_bf16 v[72:75], v[148:151], v[132:135], v[72:75]
	v_mfma_f32_16x16x32_bf16 v[84:87], v[152:155], v[116:119], v[84:87]
	v_mfma_f32_16x16x32_bf16 v[68:71], v[152:155], v[132:135], v[68:71]
	s_waitcnt lgkmcnt(2)
	v_mfma_f32_16x16x32_bf16 v[188:191], v[4:7], v[8:11], v[108:111]
	s_waitcnt vmcnt(0)
	v_mfma_f32_16x16x32_bf16 v[204:207], v[4:7], v[40:43], v[112:115]
	ds_write_b128 v168, v[56:59] offset:0
	v_mfma_f32_16x16x32_bf16 v[188:191], v[12:15], v[32:35], v[188:191]
	ds_write_b128 v168, v[60:63] offset:2048
	v_mfma_f32_16x16x32_bf16 v[204:207], v[12:15], v[44:47], v[204:207]
	ds_write_b128 v169, v[52:55] offset:8192
	v_mfma_f32_16x16x32_bf16 v[188:191], v[20:23], v[36:39], v[188:191]
	ds_write_b128 v170, v[48:51] offset:32768
	v_mfma_f32_16x16x32_bf16 v[204:207], v[20:23], v[16:19], v[204:207]
	ds_write_b128 v170, v[64:67] offset:36864
	v_mfma_f32_16x16x32_bf16 v[104:107], v[248:251], v[124:127], v[104:107]
	global_load_dwordx4 v[48:51], v[164:165], off offset:128
	s_mov_b64 s[0:1], 0x10000
	v_lshl_add_u64 v[212:213], v[164:165], 0, s[0:1]
	global_load_dwordx4 v[64:67], v[212:213], off offset:128
	v_mfma_f32_16x16x32_bf16 v[88:91], v[248:251], v[140:143], v[88:91]
	s_mov_b64 s[0:1], 0x20000
	v_lshl_add_u64 v[164:165], v[164:165], 0, s[0:1]
	global_load_dwordx4 v[56:59], v[164:165], off
	s_mov_b64 s[0:1], 0x10000
	v_mfma_f32_16x16x32_bf16 v[100:103], v[208:211], v[124:127], v[100:103]
	v_lshl_add_u64 v[212:213], v[164:165], 0, s[0:1]
	global_load_dwordx4 v[60:63], v[212:213], off
	global_load_dwordx4 v[52:55], v[160:161], off
	s_mov_b64 s[0:1], 0xe4000
	v_mfma_f32_16x16x32_bf16 v[80:83], v[208:211], v[140:143], v[80:83]
	v_lshl_add_u64 v[160:161], v[160:161], 0, s[0:1]
	v_max3_f32 v2, v176, v177, v178
	v_max3_f32 v3, v192, v193, v194
	v_max3_f32 v2, v2, v179, v180
	v_mfma_f32_16x16x32_bf16 v[96:99], v[240:243], v[124:127], v[96:99]
	v_max3_f32 v3, v3, v195, v196
	v_max3_f32 v2, v2, v181, v182
	v_max3_f32 v3, v3, v197, v198
	v_max3_f32 v2, v2, v183, v184
	v_mfma_f32_16x16x32_bf16 v[76:79], v[240:243], v[140:143], v[76:79]
	v_max3_f32 v3, v3, v199, v200
	v_max3_f32 v2, v2, v185, v186
	v_max3_f32 v3, v3, v201, v202
	v_max3_f32 v2, v2, v187, v188
	v_mfma_f32_16x16x32_bf16 v[92:95], v[252:255], v[124:127], v[92:95]
	v_max3_f32 v3, v3, v203, v204
	v_max3_f32 v2, v2, v189, v190
	v_max3_f32 v3, v3, v205, v206
	v_max3_f32 v2, v2, v191, v191
	v_mfma_f32_16x16x32_bf16 v[72:75], v[252:255], v[140:143], v[72:75]
	v_max3_f32 v3, v3, v207, v207
	s_waitcnt lgkmcnt(0)
	v_mfma_f32_16x16x32_bf16 v[84:87], v[24:27], v[124:127], v[84:87]
	v_mfma_f32_16x16x32_bf16 v[68:71], v[24:27], v[140:143], v[68:71]
	s_add_i32 s57, s57, 1
	s_cmp_lt_u32 s57, s44
	s_barrier
	s_setprio 2
	s_cbranch_scc0 .Lmla_x_done

.Lmla_x_cont1:
	v_exp_f32_e32 v176, v176
	v_exp_f32_e32 v177, v177
	v_exp_f32_e32 v178, v178
	v_exp_f32_e32 v179, v179
	v_exp_f32_e32 v192, v192
	v_exp_f32_e32 v193, v193
	v_exp_f32_e32 v194, v194
	v_exp_f32_e32 v195, v195
	s_waitcnt lgkmcnt(8)
	v_exp_f32_e32 v180, v180
	v_mfma_f32_16x16x32_bf16 v[116:119], v[4:7], v[8:11], v[108:111]
	v_exp_f32_e32 v181, v181
	v_mfma_f32_16x16x32_bf16 v[132:135], v[4:7], v[40:43], v[112:115]
	v_exp_f32_e32 v182, v182
	v_mfma_f32_16x16x32_bf16 v[116:119], v[12:15], v[32:35], v[116:119]
	v_exp_f32_e32 v183, v183
	v_mfma_f32_16x16x32_bf16 v[132:135], v[12:15], v[44:47], v[132:135]
	v_exp_f32_e32 v196, v196
	v_mfma_f32_16x16x32_bf16 v[116:119], v[20:23], v[36:39], v[116:119]
	v_exp_f32_e32 v197, v197
	v_mfma_f32_16x16x32_bf16 v[132:135], v[20:23], v[16:19], v[132:135]
	v_exp_f32_e32 v198, v198
	v_exp_f32_e32 v199, v199
	ds_read_b128 v[4:7], v175 offset:1024
	ds_read_b128 v[12:15], v175 offset:5120
	ds_read_b128 v[20:23], v175 offset:9216
	v_cvt_pk_bf16_f32 v176, v176, v177
	v_cvt_pk_bf16_f32 v177, v178, v179
	v_cvt_pk_bf16_f32 v178, v180, v181
	v_cvt_pk_bf16_f32 v179, v182, v183
	v_cvt_pk_bf16_f32 v192, v192, v193
	v_cvt_pk_bf16_f32 v193, v194, v195
	v_cvt_pk_bf16_f32 v194, v196, v197
	v_cvt_pk_bf16_f32 v195, v198, v199
	s_waitcnt lgkmcnt(0)
	v_exp_f32_e32 v184, v184
	v_mfma_f32_16x16x32_bf16 v[120:123], v[4:7], v[8:11], v[108:111]
	v_exp_f32_e32 v185, v185
	v_mfma_f32_16x16x32_bf16 v[136:139], v[4:7], v[40:43], v[112:115]
	v_exp_f32_e32 v186, v186
	v_mfma_f32_16x16x32_bf16 v[120:123], v[12:15], v[32:35], v[120:123]
	v_exp_f32_e32 v187, v187
	v_mfma_f32_16x16x32_bf16 v[136:139], v[12:15], v[44:47], v[136:139]
	v_exp_f32_e32 v200, v200
	v_mfma_f32_16x16x32_bf16 v[120:123], v[20:23], v[36:39], v[120:123]
	v_exp_f32_e32 v201, v201
	v_mfma_f32_16x16x32_bf16 v[136:139], v[20:23], v[16:19], v[136:139]
	v_exp_f32_e32 v202, v202
	v_exp_f32_e32 v203, v203
	ds_read_b128 v[4:7], v175 offset:2048
	ds_read_b128 v[12:15], v175 offset:6144
	ds_read_b128 v[20:23], v175 offset:10240
	ds_read_b64_tr_b16 v[208:209], v167 offset:36864
	ds_read_b64_tr_b16 v[210:211], v167 offset:38912
	ds_read_b64_tr_b16 v[240:241], v171 offset:36864
	ds_read_b64_tr_b16 v[242:243], v171 offset:38912
	ds_read_b64_tr_b16 v[252:253], v172 offset:36864
	ds_read_b64_tr_b16 v[254:255], v172 offset:38912
	s_setprio 0
	v_mfma_f32_16x16x32_bf16 v[104:107], v[248:251], v[176:179], v[104:107]
	v_exp_f32_e32 v188, v188
	v_mfma_f32_16x16x32_bf16 v[88:91], v[248:251], v[192:195], v[88:91]
	v_exp_f32_e32 v189, v189
	v_mfma_f32_16x16x32_bf16 v[100:103], v[24:27], v[176:179], v[100:103]
	v_exp_f32_e32 v190, v190
	v_mfma_f32_16x16x32_bf16 v[80:83], v[24:27], v[192:195], v[80:83]
	v_exp_f32_e32 v191, v191
	v_mfma_f32_16x16x32_bf16 v[96:99], v[28:31], v[176:179], v[96:99]
	v_exp_f32_e32 v204, v204
	v_mfma_f32_16x16x32_bf16 v[76:79], v[28:31], v[192:195], v[76:79]
	v_exp_f32_e32 v205, v205
	s_waitcnt lgkmcnt(6)
	v_mfma_f32_16x16x32_bf16 v[124:127], v[4:7], v[8:11], v[108:111]
	v_exp_f32_e32 v206, v206
	v_exp_f32_e32 v207, v207
	v_mfma_f32_16x16x32_bf16 v[140:143], v[4:7], v[40:43], v[112:115]
	s_nop 0
	v_cvt_pk_bf16_f32 v184, v184, v185
	v_mfma_f32_16x16x32_bf16 v[124:127], v[12:15], v[32:35], v[124:127]
	v_cvt_pk_bf16_f32 v185, v186, v187
	v_cvt_pk_bf16_f32 v186, v188, v189
	v_mfma_f32_16x16x32_bf16 v[140:143], v[12:15], v[44:47], v[140:143]
	v_cvt_pk_bf16_f32 v187, v190, v191
	v_cvt_pk_bf16_f32 v200, v200, v201
	v_mfma_f32_16x16x32_bf16 v[124:127], v[20:23], v[36:39], v[124:127]
	v_cvt_pk_bf16_f32 v201, v202, v203
	v_cvt_pk_bf16_f32 v202, v204, v205
	v_mfma_f32_16x16x32_bf16 v[140:143], v[20:23], v[16:19], v[140:143]
	v_cvt_pk_bf16_f32 v203, v206, v207
	ds_read_b128 v[4:7], v175 offset:3072
	ds_read_b128 v[12:15], v175 offset:7168
	ds_read_b128 v[20:23], v175 offset:11264
	ds_read_b64_tr_b16 v[24:25], v173 offset:36864
	ds_read_b64_tr_b16 v[26:27], v173 offset:38912
	v_mfma_f32_16x16x32_bf16 v[92:95], v[148:151], v[176:179], v[92:95]
	v_mfma_f32_16x16x32_bf16 v[72:75], v[148:151], v[192:195], v[72:75]
	v_mfma_f32_16x16x32_bf16 v[84:87], v[152:155], v[176:179], v[84:87]
	v_mfma_f32_16x16x32_bf16 v[68:71], v[152:155], v[192:195], v[68:71]
	s_waitcnt lgkmcnt(2)
	v_mfma_f32_16x16x32_bf16 v[128:131], v[4:7], v[8:11], v[108:111]
	s_waitcnt vmcnt(0)
	v_mfma_f32_16x16x32_bf16 v[144:147], v[4:7], v[40:43], v[112:115]
	ds_write_b128 v168, v[56:59] offset:20480
	v_mfma_f32_16x16x32_bf16 v[128:131], v[12:15], v[32:35], v[128:131]
	ds_write_b128 v168, v[60:63] offset:22528
	v_mfma_f32_16x16x32_bf16 v[144:147], v[12:15], v[44:47], v[144:147]
	ds_write_b128 v169, v[52:55] offset:28672
	v_mfma_f32_16x16x32_bf16 v[128:131], v[20:23], v[36:39], v[128:131]
	ds_write_b128 v170, v[48:51] offset:12288
	v_mfma_f32_16x16x32_bf16 v[144:147], v[20:23], v[16:19], v[144:147]
	ds_write_b128 v170, v[64:67] offset:16384
	v_mfma_f32_16x16x32_bf16 v[104:107], v[248:251], v[184:187], v[104:107]
	global_load_dwordx4 v[48:51], v[164:165], off offset:128
	s_mov_b64 s[0:1], 0x10000
	v_lshl_add_u64 v[212:213], v[164:165], 0, s[0:1]
	global_load_dwordx4 v[64:67], v[212:213], off offset:128
	v_mfma_f32_16x16x32_bf16 v[88:91], v[248:251], v[200:203], v[88:91]
	s_mov_b64 s[0:1], 0x20000
	v_lshl_add_u64 v[164:165], v[164:165], 0, s[0:1]
	global_load_dwordx4 v[56:59], v[164:165], off
	s_mov_b64 s[0:1], 0x10000
	v_mfma_f32_16x16x32_bf16 v[100:103], v[208:211], v[184:187], v[100:103]
	v_lshl_add_u64 v[212:213], v[164:165], 0, s[0:1]
	global_load_dwordx4 v[60:63], v[212:213], off
	global_load_dwordx4 v[52:55], v[160:161], off
	s_mov_b64 s[0:1], 0xe4000
	v_mfma_f32_16x16x32_bf16 v[80:83], v[208:211], v[200:203], v[80:83]
	v_lshl_add_u64 v[160:161], v[160:161], 0, s[0:1]
	v_max3_f32 v2, v116, v117, v118
	v_max3_f32 v3, v132, v133, v134
	v_max3_f32 v2, v2, v119, v120
	v_mfma_f32_16x16x32_bf16 v[96:99], v[240:243], v[184:187], v[96:99]
	v_max3_f32 v3, v3, v135, v136
	v_max3_f32 v2, v2, v121, v122
	v_max3_f32 v3, v3, v137, v138
	v_max3_f32 v2, v2, v123, v124
	v_mfma_f32_16x16x32_bf16 v[76:79], v[240:243], v[200:203], v[76:79]
	v_max3_f32 v3, v3, v139, v140
	v_max3_f32 v2, v2, v125, v126
	v_max3_f32 v3, v3, v141, v142
	v_max3_f32 v2, v2, v127, v128
	v_mfma_f32_16x16x32_bf16 v[92:95], v[252:255], v[184:187], v[92:95]
	v_max3_f32 v3, v3, v143, v144
	v_max3_f32 v2, v2, v129, v130
	v_max3_f32 v3, v3, v145, v146
	v_max3_f32 v2, v2, v131, v131
	v_mfma_f32_16x16x32_bf16 v[72:75], v[252:255], v[200:203], v[72:75]
	v_max3_f32 v3, v3, v147, v147
	s_waitcnt lgkmcnt(0)
	v_mfma_f32_16x16x32_bf16 v[84:87], v[24:27], v[184:187], v[84:87]
	v_mfma_f32_16x16x32_bf16 v[68:71], v[24:27], v[200:203], v[68:71]
	s_add_i32 s57, s57, 1
	s_cmp_lt_u32 s57, s44
	s_barrier
	s_setprio 2
	s_cbranch_scc1 .Lmla_x_body0
.Lmla_x_done:
	s_setprio 0
	s_branch .LBB0_440
